# latent attention: K-tile LDS writes issued before the last two QK MFMAs so they drain before the tile barrier
# speedup vs baseline: 1.0096x; 1.0078x over previous
.LBB0_210:
	s_add_i32 s71, s64, 0x4000
	s_and_b32 s9, s71, 0x4000
	v_add_u32_e32 v179, s9, v177
	v_add_u32_e32 v197, v179, v176
	v_add_u32_e32 v202, v179, v175
	v_add_u32_e32 v203, v179, v173
	v_add_u32_e32 v204, v179, v171
	ds_read_b128 v[214:217], v197 offset:4096
	ds_read_b128 v[218:221], v202 offset:4096
	ds_read_b128 v[246:249], v203 offset:4096
	ds_read_b128 v[236:239], v204 offset:4096
	v_add_u32_e32 v205, s9, v174
	v_add_u32_e32 v206, v205, v176
	ds_read_b128 v[198:201], v206 offset:32768
	v_add_u32_e32 v207, v205, v175
	v_add_u32_e32 v208, v205, v173
	v_add_u32_e32 v205, v205, v171
	v_exp_f32_e32 v179, v80
	v_exp_f32_e32 v180, v81
	v_exp_f32_e32 v181, v82
	v_exp_f32_e32 v182, v83
	v_exp_f32_e32 v183, v84
	v_exp_f32_e32 v184, v85
	v_exp_f32_e32 v185, v86
	v_exp_f32_e32 v186, v87
	v_exp_f32_e32 v187, v88
	v_exp_f32_e32 v188, v89
	v_exp_f32_e32 v189, v90
	v_exp_f32_e32 v190, v91
	v_exp_f32_e32 v191, v92
	v_exp_f32_e32 v194, v93
	v_exp_f32_e32 v195, v94
	v_exp_f32_e32 v196, v95
	s_and_b32 s9, s64, 0x4000
	s_add_i32 s46, s9, 0
	v_add_u32_e32 v213, s46, v165
	s_andn2_b64 vcc, exec, s[0:1]
	s_waitcnt lgkmcnt(4)
	v_mfma_f32_32x32x16_bf16 v[80:95], v[214:217], v[112:115], v[64:79]
	ds_read_b128 v[214:217], v206 offset:36864
	v_exp_f32_e32 v209, v108
	s_waitcnt lgkmcnt(4)
	v_mfma_f32_32x32x16_bf16 v[80:95], v[218:221], v[116:119], v[80:95]
	ds_read_b128 v[218:221], v206 offset:40960
	v_exp_f32_e32 v210, v109
	s_waitcnt lgkmcnt(4)
	v_mfma_f32_32x32x16_bf16 v[80:95], v[246:249], v[120:123], v[80:95]
	ds_read_b128 v[246:249], v206 offset:45056
	v_exp_f32_e32 v206, v105
	s_waitcnt lgkmcnt(4)
	v_mfma_f32_32x32x16_bf16 v[80:95], v[236:239], v[124:127], v[80:95]
	ds_read_b128 v[236:239], v207 offset:32768
	v_exp_f32_e32 v211, v110
	s_waitcnt lgkmcnt(4)
	v_mfma_f32_32x32x16_bf16 v[48:63], v[198:201], v[148:151], v[48:63]
	ds_read_b128 v[198:201], v207 offset:36864
	v_exp_f32_e32 v212, v111
	s_waitcnt lgkmcnt(4)
	v_mfma_f32_32x32x16_bf16 v[32:47], v[214:217], v[148:151], v[32:47]
	ds_read_b128 v[214:217], v207 offset:40960
	s_waitcnt lgkmcnt(4)
	v_mfma_f32_32x32x16_bf16 v[16:31], v[218:221], v[148:151], v[16:31]
	ds_read_b128 v[218:221], v207 offset:45056
	v_exp_f32_e32 v207, v106
	s_waitcnt lgkmcnt(4)
	v_mfma_f32_32x32x16_bf16 v[0:15], v[246:249], v[148:151], v[0:15]
	ds_read_b128 v[246:249], v208 offset:32768
	s_waitcnt lgkmcnt(4)
	v_mfma_f32_32x32x16_bf16 v[48:63], v[236:239], v[144:147], v[48:63]
	ds_read_b128 v[236:239], v208 offset:36864
	s_waitcnt lgkmcnt(4)
	v_mfma_f32_32x32x16_bf16 v[32:47], v[198:201], v[144:147], v[32:47]
	ds_read_b128 v[198:201], v208 offset:40960
	s_waitcnt lgkmcnt(4)
	v_mfma_f32_32x32x16_bf16 v[16:31], v[214:217], v[144:147], v[16:31]
	ds_read_b128 v[214:217], v208 offset:45056
	v_exp_f32_e32 v208, v107
	s_waitcnt lgkmcnt(4)
	v_mfma_f32_32x32x16_bf16 v[0:15], v[218:221], v[144:147], v[0:15]
	ds_read_b128 v[218:221], v205 offset:32768
	s_waitcnt lgkmcnt(4)
	v_mfma_f32_32x32x16_bf16 v[48:63], v[246:249], v[140:143], v[48:63]
	ds_read_b128 v[246:249], v205 offset:36864
	s_waitcnt lgkmcnt(4)
	v_mfma_f32_32x32x16_bf16 v[32:47], v[236:239], v[140:143], v[32:47]
	ds_read_b128 v[236:239], v205 offset:40960
	s_waitcnt lgkmcnt(4)
	v_mfma_f32_32x32x16_bf16 v[16:31], v[198:201], v[140:143], v[16:31]
	ds_read_b128 v[148:151], v205 offset:45056
	v_exp_f32_e32 v205, v104
	v_exp_f32_e32 v198, v97
	v_exp_f32_e32 v199, v98
	s_waitcnt lgkmcnt(4)
	v_mfma_f32_32x32x16_bf16 v[0:15], v[214:217], v[140:143], v[0:15]
	ds_read_b128 v[214:217], v197
	v_exp_f32_e32 v197, v96
	v_exp_f32_e32 v200, v99
	v_exp_f32_e32 v201, v100
	s_waitcnt lgkmcnt(4)
	v_mfma_f32_32x32x16_bf16 v[48:63], v[218:221], v[136:139], v[48:63]
	ds_read_b128 v[218:221], v202
	v_exp_f32_e32 v202, v101
	v_add_f32_e32 v222, v197, v179
	v_add_f32_e32 v223, 0, v222
	v_add_f32_e32 v222, v198, v180
	v_add_f32_e32 v223, v222, v223
	v_add_f32_e32 v222, v199, v181
	v_add_f32_e32 v223, v222, v223
	s_waitcnt lgkmcnt(4)
	v_mfma_f32_32x32x16_bf16 v[32:47], v[246:249], v[136:139], v[32:47]
	ds_read_b128 v[246:249], v203
	v_exp_f32_e32 v203, v102
	v_add_f32_e32 v222, v200, v182
	v_add_f32_e32 v223, v222, v223
	v_add_f32_e32 v222, v201, v183
	v_add_f32_e32 v223, v222, v223
	v_add_f32_e32 v222, v202, v184
	v_add_f32_e32 v223, v222, v223
	s_waitcnt lgkmcnt(4)
	v_mfma_f32_32x32x16_bf16 v[16:31], v[236:239], v[136:139], v[16:31]
	ds_read_b128 v[236:239], v204
	v_exp_f32_e32 v204, v103
	v_add_f32_e32 v222, v203, v185
	v_add_f32_e32 v223, v222, v223
	s_waitcnt lgkmcnt(4)
	v_mfma_f32_32x32x16_bf16 v[0:15], v[148:151], v[136:139], v[0:15]
	v_add_f32_e32 v222, v204, v186
	v_add_f32_e32 v223, v222, v223
	v_cvt_pk_bf16_f32 v148, v197, v198
	v_cvt_pk_bf16_f32 v149, v199, v200
	v_cvt_pk_bf16_f32 v150, v201, v202
	v_cvt_pk_bf16_f32 v151, v203, v204
	v_cvt_pk_bf16_f32 v140, v179, v180
	v_cvt_pk_bf16_f32 v141, v181, v182
	v_cvt_pk_bf16_f32 v142, v183, v184
	s_waitcnt lgkmcnt(3)
	v_mfma_f32_32x32x16_bf16 v[96:111], v[214:217], v[112:115], v[64:79]
	v_add_f32_e32 v222, v205, v187
	v_add_f32_e32 v223, v222, v223
	v_add_f32_e32 v222, v206, v188
	v_add_f32_e32 v223, v222, v223
	v_add_f32_e32 v222, v207, v189
	v_add_f32_e32 v223, v222, v223
	v_add_f32_e32 v222, v208, v190
	v_add_f32_e32 v223, v222, v223
	v_add_u32_e32 v214, v213, v172
	v_cvt_pk_bf16_f32 v143, v185, v186
	v_cvt_pk_bf16_f32 v144, v205, v206
	v_cvt_pk_bf16_f32 v145, v207, v208
	v_cvt_pk_bf16_f32 v146, v209, v210
	v_cvt_pk_bf16_f32 v147, v211, v212
	v_cvt_pk_bf16_f32 v136, v187, v188
	s_waitcnt lgkmcnt(2)
	v_mfma_f32_32x32x16_bf16 v[96:111], v[218:221], v[116:119], v[96:111]
	v_add_f32_e32 v222, v209, v191
	v_add_f32_e32 v223, v222, v223
	v_add_f32_e32 v222, v210, v194
	v_add_f32_e32 v223, v222, v223
	v_add_f32_e32 v222, v211, v195
	v_add_f32_e32 v223, v222, v223
	v_add_f32_e32 v222, v212, v196
	v_add_f32_e32 v223, v222, v223
	v_add_f32_e32 v168, v168, v223
	v_cvt_pk_bf16_f32 v137, v189, v190
	v_cvt_pk_bf16_f32 v138, v191, v194
	v_cvt_pk_bf16_f32 v139, v195, v196
	s_waitcnt vmcnt(1)
	ds_write_b64 v214, v[152:153] offset:32768
	v_add_u32_e32 v152, v213, v169
	s_waitcnt vmcnt(0)
	ds_write_b64 v214, v[156:157] offset:40960
	ds_write2st64_b64 v152, v[154:155], v[158:159] offset0:64 offset1:80
	s_cbranch_vccnz .Lattn_nokw
	v_add_u32_e32 v152, s46, v170
	ds_write_b128 v152, v[128:131]
	ds_write_b128 v152, v[132:135] offset:8192
.Lattn_nokw:
	s_waitcnt lgkmcnt(4)
	v_mfma_f32_32x32x16_bf16 v[96:111], v[246:249], v[120:123], v[96:111]
	s_waitcnt lgkmcnt(3)
	v_mfma_f32_32x32x16_bf16 v[96:111], v[236:239], v[124:127], v[96:111]
